# grid-barrier poll loop: s_sleep 1 between generation-word polls replaced by s_nop 7 (shorter release detection)
# speedup vs baseline: 1.0006x; 1.0006x over previous
; DI unsigned xb_ld(unsigned* p)              { return __hip_atomic_load(p, __ATOMIC_RELAXED, __HIP_MEMORY_SCOPE_AGENT); }
; DI unsigned xb_add(unsigned* p, unsigned v) { return __hip_atomic_fetch_add(p, v, __ATOMIC_RELAXED, __HIP_MEMORY_SCOPE_AGENT); }
; #define XB_SPIN(cond, bar) do { unsigned _sp = 0; while (cond) { __builtin_amdgcn_s_sleep(1); \
;     if ((++_sp & 255u) == 0u) { if (xb_ld(&(bar)[XB_TMO])) break; if (_sp > XB_SPIN_CAP) { atomicAdd(&(bar)[XB_TMO], 1u); break; } } } } while (0)
; DI void xcd_barrier(const XcdBarrier& b) {
;     ...
;             else XB_SPIN(xb_ld(&bar[XB_TOPGEN]) == tg, bar);
;             __builtin_amdgcn_fence(__ATOMIC_ACQUIRE, "agent");
;             xb_add(&bar[XB_XGEN(b.x)], 1u);
;             asm volatile("s_waitcnt vmcnt(0)" ::: "memory");
;         } else {
;             XB_SPIN(xb_ld(&bar[XB_XGEN(b.x)]) == gen, bar);
.Lmb1_spin:
	global_load_dword v4, v0, s[10:11] sc1
	s_waitcnt vmcnt(0)
	v_readfirstlane_b32 s3, v4
	s_cmp_gt_u32 s3, 0
	s_cbranch_scc1 .Lmb1_got
	s_add_i32 s23, s23, 1
	s_cmp_lt_u32 s23, 0x40000
	s_cbranch_scc0 .Lmb1_got
	s_nop 7
	s_branch .Lmb1_spin

; DI unsigned xb_ld(unsigned* p)              { return __hip_atomic_load(p, __ATOMIC_RELAXED, __HIP_MEMORY_SCOPE_AGENT); }
; DI unsigned xb_add(unsigned* p, unsigned v) { return __hip_atomic_fetch_add(p, v, __ATOMIC_RELAXED, __HIP_MEMORY_SCOPE_AGENT); }
; #define XB_SPIN(cond, bar) do { unsigned _sp = 0; while (cond) { __builtin_amdgcn_s_sleep(1); \
;     if ((++_sp & 255u) == 0u) { if (xb_ld(&(bar)[XB_TMO])) break; if (_sp > XB_SPIN_CAP) { atomicAdd(&(bar)[XB_TMO], 1u); break; } } } } while (0)
; #define SEAM(k) do { if (IN(k) && IN((k) + 1)) xcd_barrier(bar); } while (0)
; DI void xcd_barrier(const XcdBarrier& b) {
;     ...
;             else XB_SPIN(xb_ld(&bar[XB_TOPGEN]) == tg, bar);
;             __builtin_amdgcn_fence(__ATOMIC_ACQUIRE, "agent");
;             xb_add(&bar[XB_XGEN(b.x)], 1u);
;             asm volatile("s_waitcnt vmcnt(0)" ::: "memory");
;         } else {
;             XB_SPIN(xb_ld(&bar[XB_XGEN(b.x)]) == gen, bar);
; __global__ void __launch_bounds__(512, 2) fwd_kernel(Args a) {
;     ...
;     SEAM(1);
.Lmb2_spin:
	global_load_dword v4, v0, s[10:11] sc1
	s_waitcnt vmcnt(0)
	v_readfirstlane_b32 s3, v4
	s_cmp_gt_u32 s3, 1
	s_cbranch_scc1 .Lmb2_got
	s_add_i32 s23, s23, 1
	s_cmp_lt_u32 s23, 0x40000
	s_cbranch_scc0 .Lmb2_got
	s_nop 7
	s_branch .Lmb2_spin

; DI unsigned xb_ld(unsigned* p)              { return __hip_atomic_load(p, __ATOMIC_RELAXED, __HIP_MEMORY_SCOPE_AGENT); }
; DI unsigned xb_add(unsigned* p, unsigned v) { return __hip_atomic_fetch_add(p, v, __ATOMIC_RELAXED, __HIP_MEMORY_SCOPE_AGENT); }
; #define XB_SPIN(cond, bar) do { unsigned _sp = 0; while (cond) { __builtin_amdgcn_s_sleep(1); \
;     if ((++_sp & 255u) == 0u) { if (xb_ld(&(bar)[XB_TMO])) break; if (_sp > XB_SPIN_CAP) { atomicAdd(&(bar)[XB_TMO], 1u); break; } } } } while (0)
; #define SEAM(k) do { if (IN(k) && IN((k) + 1)) xcd_barrier(bar); } while (0)
; DI void xcd_barrier(const XcdBarrier& b) {
;     ...
;             else XB_SPIN(xb_ld(&bar[XB_TOPGEN]) == tg, bar);
;             __builtin_amdgcn_fence(__ATOMIC_ACQUIRE, "agent");
;             xb_add(&bar[XB_XGEN(b.x)], 1u);
;             asm volatile("s_waitcnt vmcnt(0)" ::: "memory");
;         } else {
;             XB_SPIN(xb_ld(&bar[XB_XGEN(b.x)]) == gen, bar);
; __global__ void __launch_bounds__(512, 2) fwd_kernel(Args a) {
;     ...
;     SEAM(3);
.Lmb4_spin:
	global_load_dword v4, v0, s[10:11] sc1
	s_waitcnt vmcnt(0)
	v_readfirstlane_b32 s3, v4
	s_cmp_gt_u32 s3, 2
	s_cbranch_scc1 .Lmb4_got
	s_add_i32 s23, s23, 1
	s_cmp_lt_u32 s23, 0x40000
	s_cbranch_scc0 .Lmb4_got
	s_nop 7
	s_branch .Lmb4_spin

; DI unsigned xb_ld(unsigned* p)              { return __hip_atomic_load(p, __ATOMIC_RELAXED, __HIP_MEMORY_SCOPE_AGENT); }
; DI unsigned xb_add(unsigned* p, unsigned v) { return __hip_atomic_fetch_add(p, v, __ATOMIC_RELAXED, __HIP_MEMORY_SCOPE_AGENT); }
; #define XB_SPIN(cond, bar) do { unsigned _sp = 0; while (cond) { __builtin_amdgcn_s_sleep(1); \
;     if ((++_sp & 255u) == 0u) { if (xb_ld(&(bar)[XB_TMO])) break; if (_sp > XB_SPIN_CAP) { atomicAdd(&(bar)[XB_TMO], 1u); break; } } } } while (0)
; #define SEAM(k) do { if (IN(k) && IN((k) + 1)) xcd_barrier(bar); } while (0)
; DI void xcd_barrier(const XcdBarrier& b) {
;     ...
;             else XB_SPIN(xb_ld(&bar[XB_TOPGEN]) == tg, bar);
;             __builtin_amdgcn_fence(__ATOMIC_ACQUIRE, "agent");
;             xb_add(&bar[XB_XGEN(b.x)], 1u);
;             asm volatile("s_waitcnt vmcnt(0)" ::: "memory");
;         } else {
;             XB_SPIN(xb_ld(&bar[XB_XGEN(b.x)]) == gen, bar);
; __global__ void __launch_bounds__(512, 2) fwd_kernel(Args a) {
;     ...
;     SEAM(4);
.Lmb5_spin:
	global_load_dword v4, v0, s[10:11] sc1
	s_waitcnt vmcnt(0)
	v_readfirstlane_b32 s3, v4
	s_cmp_gt_u32 s3, 3
	s_cbranch_scc1 .Lmb5_got
	s_add_i32 s23, s23, 1
	s_cmp_lt_u32 s23, 0x40000
	s_cbranch_scc0 .Lmb5_got
	s_nop 7
	s_branch .Lmb5_spin

; DI unsigned xb_ld(unsigned* p)              { return __hip_atomic_load(p, __ATOMIC_RELAXED, __HIP_MEMORY_SCOPE_AGENT); }
; DI unsigned xb_add(unsigned* p, unsigned v) { return __hip_atomic_fetch_add(p, v, __ATOMIC_RELAXED, __HIP_MEMORY_SCOPE_AGENT); }
; #define XB_SPIN(cond, bar) do { unsigned _sp = 0; while (cond) { __builtin_amdgcn_s_sleep(1); \
;     if ((++_sp & 255u) == 0u) { if (xb_ld(&(bar)[XB_TMO])) break; if (_sp > XB_SPIN_CAP) { atomicAdd(&(bar)[XB_TMO], 1u); break; } } } } while (0)
; #define SEAM(k) do { if (IN(k) && IN((k) + 1)) xcd_barrier(bar); } while (0)
; DI void xcd_barrier(const XcdBarrier& b) {
;     ...
;             else XB_SPIN(xb_ld(&bar[XB_TOPGEN]) == tg, bar);
;             __builtin_amdgcn_fence(__ATOMIC_ACQUIRE, "agent");
;             xb_add(&bar[XB_XGEN(b.x)], 1u);
;             asm volatile("s_waitcnt vmcnt(0)" ::: "memory");
;         } else {
;             XB_SPIN(xb_ld(&bar[XB_XGEN(b.x)]) == gen, bar);
; __global__ void __launch_bounds__(512, 2) fwd_kernel(Args a) {
;     ...
;     SEAM(5);
.Lmb6_spin:
	global_load_dword v4, v0, s[10:11] sc1
	s_waitcnt vmcnt(0)
	v_readfirstlane_b32 s3, v4
	s_cmp_gt_u32 s3, 4
	s_cbranch_scc1 .Lmb6_got
	s_add_i32 s23, s23, 1
	s_cmp_lt_u32 s23, 0x40000
	s_cbranch_scc0 .Lmb6_got
	s_nop 7
	s_branch .Lmb6_spin

; DI unsigned xb_ld(unsigned* p)              { return __hip_atomic_load(p, __ATOMIC_RELAXED, __HIP_MEMORY_SCOPE_AGENT); }
; DI unsigned xb_add(unsigned* p, unsigned v) { return __hip_atomic_fetch_add(p, v, __ATOMIC_RELAXED, __HIP_MEMORY_SCOPE_AGENT); }
; #define XB_SPIN(cond, bar) do { unsigned _sp = 0; while (cond) { __builtin_amdgcn_s_sleep(1); \
;     if ((++_sp & 255u) == 0u) { if (xb_ld(&(bar)[XB_TMO])) break; if (_sp > XB_SPIN_CAP) { atomicAdd(&(bar)[XB_TMO], 1u); break; } } } } while (0)
; #define SEAM(k) do { if (IN(k) && IN((k) + 1)) xcd_barrier(bar); } while (0)
; DI void xcd_barrier(const XcdBarrier& b) {
;     ...
;             else XB_SPIN(xb_ld(&bar[XB_TOPGEN]) == tg, bar);
;             __builtin_amdgcn_fence(__ATOMIC_ACQUIRE, "agent");
;             xb_add(&bar[XB_XGEN(b.x)], 1u);
;             asm volatile("s_waitcnt vmcnt(0)" ::: "memory");
;         } else {
;             XB_SPIN(xb_ld(&bar[XB_XGEN(b.x)]) == gen, bar);
; __global__ void __launch_bounds__(512, 2) fwd_kernel(Args a) {
;     ...
;     SEAM(6);
.Lmb7_spin:
	global_load_dword v4, v0, s[10:11] sc1
	s_waitcnt vmcnt(0)
	v_readfirstlane_b32 s3, v4
	s_cmp_gt_u32 s3, 5
	s_cbranch_scc1 .Lmb7_got
	s_add_i32 s23, s23, 1
	s_cmp_lt_u32 s23, 0x40000
	s_cbranch_scc0 .Lmb7_got
	s_nop 7
	s_branch .Lmb7_spin

; DI unsigned xb_ld(unsigned* p)              { return __hip_atomic_load(p, __ATOMIC_RELAXED, __HIP_MEMORY_SCOPE_AGENT); }
; DI unsigned xb_add(unsigned* p, unsigned v) { return __hip_atomic_fetch_add(p, v, __ATOMIC_RELAXED, __HIP_MEMORY_SCOPE_AGENT); }
; #define XB_SPIN(cond, bar) do { unsigned _sp = 0; while (cond) { __builtin_amdgcn_s_sleep(1); \
;     if ((++_sp & 255u) == 0u) { if (xb_ld(&(bar)[XB_TMO])) break; if (_sp > XB_SPIN_CAP) { atomicAdd(&(bar)[XB_TMO], 1u); break; } } } } while (0)
; #define SEAM(k) do { if (IN(k) && IN((k) + 1)) xcd_barrier(bar); } while (0)
; DI void xcd_barrier(const XcdBarrier& b) {
;     ...
;             else XB_SPIN(xb_ld(&bar[XB_TOPGEN]) == tg, bar);
;             __builtin_amdgcn_fence(__ATOMIC_ACQUIRE, "agent");
;             xb_add(&bar[XB_XGEN(b.x)], 1u);
;             asm volatile("s_waitcnt vmcnt(0)" ::: "memory");
;         } else {
;             XB_SPIN(xb_ld(&bar[XB_XGEN(b.x)]) == gen, bar);
; __global__ void __launch_bounds__(512, 2) fwd_kernel(Args a) {
;     ...
;     SEAM(7);
.Lmb8_spin:
	global_load_dword v4, v0, s[10:11] sc1
	s_waitcnt vmcnt(0)
	v_readfirstlane_b32 s3, v4
	s_cmp_gt_u32 s3, 6
	s_cbranch_scc1 .Lmb8_got
	s_add_i32 s23, s23, 1
	s_cmp_lt_u32 s23, 0x40000
	s_cbranch_scc0 .Lmb8_got
	s_nop 7
	s_branch .Lmb8_spin

; DI unsigned xb_ld(unsigned* p)              { return __hip_atomic_load(p, __ATOMIC_RELAXED, __HIP_MEMORY_SCOPE_AGENT); }
; DI unsigned xb_add(unsigned* p, unsigned v) { return __hip_atomic_fetch_add(p, v, __ATOMIC_RELAXED, __HIP_MEMORY_SCOPE_AGENT); }
; #define XB_SPIN(cond, bar) do { unsigned _sp = 0; while (cond) { __builtin_amdgcn_s_sleep(1); \
;     if ((++_sp & 255u) == 0u) { if (xb_ld(&(bar)[XB_TMO])) break; if (_sp > XB_SPIN_CAP) { atomicAdd(&(bar)[XB_TMO], 1u); break; } } } } while (0)
; #define SEAM(k) do { if (IN(k) && IN((k) + 1)) xcd_barrier(bar); } while (0)
; DI void xcd_barrier(const XcdBarrier& b) {
;     ...
;             else XB_SPIN(xb_ld(&bar[XB_TOPGEN]) == tg, bar);
;             __builtin_amdgcn_fence(__ATOMIC_ACQUIRE, "agent");
;             xb_add(&bar[XB_XGEN(b.x)], 1u);
;             asm volatile("s_waitcnt vmcnt(0)" ::: "memory");
;         } else {
;             XB_SPIN(xb_ld(&bar[XB_XGEN(b.x)]) == gen, bar);
; __global__ void __launch_bounds__(512, 2) fwd_kernel(Args a) {
;     ...
;     SEAM(8);
.Lmb9_spin:
	global_load_dword v4, v0, s[10:11] sc1
	s_waitcnt vmcnt(0)
	v_readfirstlane_b32 s3, v4
	s_cmp_gt_u32 s3, 7
	s_cbranch_scc1 .Lmb9_got
	s_add_i32 s23, s23, 1
	s_cmp_lt_u32 s23, 0x40000
	s_cbranch_scc0 .Lmb9_got
	s_nop 7
	s_branch .Lmb9_spin

; DI unsigned xb_ld(unsigned* p)              { return __hip_atomic_load(p, __ATOMIC_RELAXED, __HIP_MEMORY_SCOPE_AGENT); }
; DI unsigned xb_add(unsigned* p, unsigned v) { return __hip_atomic_fetch_add(p, v, __ATOMIC_RELAXED, __HIP_MEMORY_SCOPE_AGENT); }
; #define XB_SPIN(cond, bar) do { unsigned _sp = 0; while (cond) { __builtin_amdgcn_s_sleep(1); \
;     if ((++_sp & 255u) == 0u) { if (xb_ld(&(bar)[XB_TMO])) break; if (_sp > XB_SPIN_CAP) { atomicAdd(&(bar)[XB_TMO], 1u); break; } } } } while (0)
; #define SEAM(k) do { if (IN(k) && IN((k) + 1)) xcd_barrier(bar); } while (0)
; DI void xcd_barrier(const XcdBarrier& b) {
;     ...
;             else XB_SPIN(xb_ld(&bar[XB_TOPGEN]) == tg, bar);
;             __builtin_amdgcn_fence(__ATOMIC_ACQUIRE, "agent");
;             xb_add(&bar[XB_XGEN(b.x)], 1u);
;             asm volatile("s_waitcnt vmcnt(0)" ::: "memory");
;         } else {
;             XB_SPIN(xb_ld(&bar[XB_XGEN(b.x)]) == gen, bar);
; __global__ void __launch_bounds__(512, 2) fwd_kernel(Args a) {
;     ...
;     SEAM(9);
.Lmb10_spin:
	global_load_dword v4, v0, s[10:11] sc1
	s_waitcnt vmcnt(0)
	v_readfirstlane_b32 s3, v4
	s_cmp_gt_u32 s3, 8
	s_cbranch_scc1 .Lmb10_got
	s_add_i32 s23, s23, 1
	s_cmp_lt_u32 s23, 0x40000
	s_cbranch_scc0 .Lmb10_got
	s_nop 7
	s_branch .Lmb10_spin
